# flat-release grid barrier + L1 invalidate issued right after the block's arrival (overlaps the wait) instead of after release
# speedup vs baseline: 1.0431x; 1.0181x over previous
.Lxbp_0:
	buffer_inv sc1
	s_mov_b32 s98, 0

.Lxbd_0:
	s_nop 0
	s_waitcnt vmcnt(0)

.Lxbd_10:
	s_nop 0
	s_waitcnt vmcnt(0)
	v_readlane_b32 s96, v254, 56
	v_readlane_b32 s97, v254, 57
	s_nop 4
